# speedup vs baseline: 1.0096x; 1.0096x over previous
; __device__ __forceinline__ void xcd_barrier(const XcdBarrier& b, unsigned epoch) {
;     asm volatile("s_waitcnt vmcnt(0)" ::: "memory");
;     __syncthreads();
; __global__ void __launch_bounds__(512, 2) mega(Params p) {
;     ...
;         phase_GC(p, l);
;         xcd_barrier(xb, e0 + 2u);
.LBB0_367:
	s_waitcnt vmcnt(0)
	v_mov_b32_e32 v0, v208
	s_barrier
	s_nop 0
	v_cmp_eq_u32_e32 vcc, 0, v0
	s_and_saveexec_b64 s[0:1], vcc
	s_cbranch_execz .LBB0_456
	v_readlane_b32 s4, v234, 46
	s_lshl_b32 s4, s4, 8
	s_and_b32 s5, s50, 63
	s_add_i32 s4, s4, s5
	s_add_i32 s4, s4, 0
	s_lshl_b32 s4, s4, 6
	s_add_i32 s4, s4, 0x4000
	s_add_u32 s4, s92, s4
	s_addc_u32 s5, s93, 0
	v_mov_b32_e32 v0, 0
	s_waitcnt vmcnt(0) lgkmcnt(0)
	s_and_b32 s6, s51, 7
	s_mul_i32 s6, s6, 3
	s_add_i32 s6, s6, 8
	s_lshl_b32 s6, 1, s6
	s_add_i32 s6, s6, 1
	v_mov_b32_e32 v2, s6
	global_atomic_add v0, v2, s[4:5]
	s_waitcnt vmcnt(0)

; __device__ __forceinline__ unsigned xb_ld(unsigned* p) { return __hip_atomic_load(p, __ATOMIC_RELAXED, __HIP_MEMORY_SCOPE_AGENT); }
; __device__ __forceinline__ unsigned xb_add(unsigned* p, unsigned v) { return __hip_atomic_fetch_add(p, v, __ATOMIC_RELAXED, __HIP_MEMORY_SCOPE_AGENT); }
; __device__ __forceinline__ void xcd_barrier(const XcdBarrier& b, unsigned epoch) {
;     ...
;         const unsigned old = xb_add(&bar[XB_XSUB(bx)], 1u);
;         const unsigned gen = epoch;
;         if (old + 1u == (gen + 1u) * bnloc) {
;             __builtin_amdgcn_fence(__ATOMIC_RELEASE, "agent");
;             asm volatile("s_waitcnt vmcnt(0)" ::: "memory");
;             const unsigned og = xb_add(&bar[XB_TOP], 1u);
;             const unsigned tg = epoch;
;             if (og + 1u == (tg + 1u) * bnx) xb_add(&bar[XB_TOPGEN], 1u);
;             else XB_SPIN(xb_ld(&bar[XB_TOPGEN]) == tg, bar);
;             __builtin_amdgcn_fence(__ATOMIC_ACQUIRE, "agent");
;             xb_add(&bar[XB_XGEN(bx)], 1u);
.Lgba_done:
	v_lshrrev_b32_e32 v3, 8, v1
	v_add_u32_e32 v2, -1, v3
	v_and_b32_e32 v2, v2, v3
	v_cmp_ne_u32_e32 vcc, 0, v2
	s_cbranch_vccz .Lgba_fast
	buffer_wbl2 sc1
	s_waitcnt vmcnt(0)
	v_readlane_b32 s4, v234, 46
	s_nop 0
	s_lshl_b32 s4, s4, 6
	s_and_b32 s5, s50, 63
	s_add_i32 s4, s4, s5
	s_lshl_b32 s4, s4, 2
	s_add_i32 s4, s4, 0xf000
	s_add_u32 s4, s92, s4
	s_addc_u32 s5, s93, 0
	global_atomic_add v0, v210, s[4:5]
	s_waitcnt vmcnt(0)

; __device__ __forceinline__ void phase_GC(const Params& p, int l) {
;     ...
;                     DOK(q0, p0, 0) DOK(q1, p1, 1) DOK(q2, p2, 2) DOK(q3, p3, 3) DOK(q4, p4, 4) DOK(q5, p5, 5) DOK(q6, p6, 6) DOK(q7, p7, 7)
.LBB0_400:
	s_andn2_b64 vcc, exec, s[0:1]
	s_cbranch_vccnz .LBB0_402
	v_lshl_add_u64 v[60:61], s[12:13], 0, v[128:129]
	global_store_dwordx4 v[60:61], v[28:31], off
	s_nop 1

; __device__ __forceinline__ void phase_GC(const Params& p, int l) {
;     ...
;                     DOK(q0, p0, 0) DOK(q1, p1, 1) DOK(q2, p2, 2) DOK(q3, p3, 3) DOK(q4, p4, 4) DOK(q5, p5, 5) DOK(q6, p6, 6) DOK(q7, p7, 7)
.LBB0_404:
	s_andn2_b64 vcc, exec, s[0:1]
	s_cbranch_vccnz .LBB0_406
	v_mov_b32_e32 v57, v129
	v_lshl_add_u64 v[28:29], s[12:13], 0, v[56:57]
	global_store_dwordx4 v[28:29], v[24:27], off
	s_nop 1

; __device__ __forceinline__ void phase_GC(const Params& p, int l) {
;     ...
;                     DOK(q0, p0, 0) DOK(q1, p1, 1) DOK(q2, p2, 2) DOK(q3, p3, 3) DOK(q4, p4, 4) DOK(q5, p5, 5) DOK(q6, p6, 6) DOK(q7, p7, 7)
.LBB0_408:
	s_andn2_b64 vcc, exec, s[0:1]
	s_cbranch_vccnz .LBB0_410
	v_mov_b32_e32 v53, v129
	v_lshl_add_u64 v[24:25], s[12:13], 0, v[52:53]
	global_store_dwordx4 v[24:25], v[20:23], off
	s_nop 1

; __device__ __forceinline__ void phase_GC(const Params& p, int l) {
;     ...
;                     DOK(q0, p0, 0) DOK(q1, p1, 1) DOK(q2, p2, 2) DOK(q3, p3, 3) DOK(q4, p4, 4) DOK(q5, p5, 5) DOK(q6, p6, 6) DOK(q7, p7, 7)
.LBB0_412:
	s_andn2_b64 vcc, exec, s[0:1]
	s_cbranch_vccnz .LBB0_414
	v_mov_b32_e32 v49, v129
	v_lshl_add_u64 v[20:21], s[12:13], 0, v[48:49]
	global_store_dwordx4 v[20:21], v[16:19], off
	s_nop 1

; __device__ __forceinline__ void phase_GC(const Params& p, int l) {
;     ...
;                     DOK(q0, p0, 0) DOK(q1, p1, 1) DOK(q2, p2, 2) DOK(q3, p3, 3) DOK(q4, p4, 4) DOK(q5, p5, 5) DOK(q6, p6, 6) DOK(q7, p7, 7)
.LBB0_416:
	s_andn2_b64 vcc, exec, s[0:1]
	s_cbranch_vccnz .LBB0_418
	v_mov_b32_e32 v45, v129
	v_lshl_add_u64 v[16:17], s[12:13], 0, v[44:45]
	global_store_dwordx4 v[16:17], v[12:15], off
	s_nop 1

; __device__ __forceinline__ void phase_GC(const Params& p, int l) {
;     ...
;                     DOK(q0, p0, 0) DOK(q1, p1, 1) DOK(q2, p2, 2) DOK(q3, p3, 3) DOK(q4, p4, 4) DOK(q5, p5, 5) DOK(q6, p6, 6) DOK(q7, p7, 7)
.LBB0_420:
	s_andn2_b64 vcc, exec, s[0:1]
	s_cbranch_vccnz .LBB0_422
	v_mov_b32_e32 v41, v129
	v_lshl_add_u64 v[12:13], s[12:13], 0, v[40:41]
	global_store_dwordx4 v[12:13], v[8:11], off
	s_nop 1

; __device__ __forceinline__ void phase_GC(const Params& p, int l) {
;     ...
;                     DOK(q0, p0, 0) DOK(q1, p1, 1) DOK(q2, p2, 2) DOK(q3, p3, 3) DOK(q4, p4, 4) DOK(q5, p5, 5) DOK(q6, p6, 6) DOK(q7, p7, 7)
.LBB0_424:
	s_andn2_b64 vcc, exec, s[0:1]
	s_cbranch_vccnz .LBB0_426
	v_mov_b32_e32 v37, v129
	v_lshl_add_u64 v[8:9], s[12:13], 0, v[36:37]
	global_store_dwordx4 v[8:9], v[4:7], off
	s_nop 1

; __device__ __forceinline__ void phase_GC(const Params& p, int l) {
;     ...
;                     DOK(q0, p0, 0) DOK(q1, p1, 1) DOK(q2, p2, 2) DOK(q3, p3, 3) DOK(q4, p4, 4) DOK(q5, p5, 5) DOK(q6, p6, 6) DOK(q7, p7, 7)
.LBB0_428:
	s_andn2_b64 vcc, exec, s[0:1]
	s_cbranch_vccnz .LBB0_381
	v_mov_b32_e32 v33, v129
	v_lshl_add_u64 v[4:5], s[12:13], 0, v[32:33]
	global_store_dwordx4 v[4:5], v[0:3], off
	s_nop 1
	s_branch .LBB0_381

; __device__ __forceinline__ int tid_opaque() { int t = threadIdx.x; asm volatile("" : "+v"(t)); return t; }
; __device__ __forceinline__ void phase_D(const Params& p, int l) {
;     ...
;         {
;             const int rt = tid_opaque();
;             const int c16 = rt & 31, r0 = rt >> 5;
;             bf16_t* ob = P1 + (long)brow * P1W + 2560 + bcol + c16 * 8;
; #pragma unroll 4
;             for (int k = 0; k < 16; ++k) {
;                 const int row = r0 + 16 * k;
;                 st16_wt(ob + (long)row * P1W, epi_read(row, c16));
;             }
;         }
;         __syncthreads();
;     }
; __global__ void __launch_bounds__(512, 2) mega(Params p) {
;     ...
;         phase_D(p, l);
;         xcd_barrier(xb, e0 + 3u);
.LBB0_480:
	ds_read_b128 v[4:7], v2
	v_lshl_add_u64 v[10:11], v[0:1], 0, s[0:1]
	v_lshl_add_u64 v[12:13], v[10:11], 0, s[82:83]
	s_add_u32 s0, s0, 0x80000
	s_addc_u32 s1, s1, 0
	s_waitcnt lgkmcnt(0)
	v_cndmask_b32_e32 v8, v4, v6, vcc
	v_cndmask_b32_e32 v9, v5, v7, vcc
	v_cndmask_b32_e32 v7, v7, v5, vcc
	v_cndmask_b32_e32 v6, v6, v4, vcc
	global_store_dwordx4 v[10:11], v[6:9], off
	s_nop 1
	ds_read_b128 v[4:7], v2 offset:8192
	s_cmp_eq_u32 s0, 0x200000
	s_waitcnt lgkmcnt(0)
	v_cndmask_b32_e32 v8, v4, v6, vcc
	v_cndmask_b32_e32 v9, v5, v7, vcc
	v_cndmask_b32_e32 v7, v7, v5, vcc
	v_cndmask_b32_e32 v6, v6, v4, vcc
	global_store_dwordx4 v[12:13], v[6:9], off
	s_nop 1
	ds_read_b128 v[4:7], v2 offset:16384
	v_lshl_add_u64 v[12:13], v[10:11], 0, s[88:89]
	v_lshl_add_u64 v[10:11], v[10:11], 0, s[86:87]
	s_waitcnt lgkmcnt(0)
	v_cndmask_b32_e32 v8, v4, v6, vcc
	v_cndmask_b32_e32 v9, v5, v7, vcc
	v_cndmask_b32_e32 v7, v7, v5, vcc
	v_cndmask_b32_e32 v6, v6, v4, vcc
	global_store_dwordx4 v[12:13], v[6:9], off
	s_nop 1
	ds_read_b128 v[4:7], v2 offset:24576
	v_add_u32_e32 v2, 0x8000, v2
	s_waitcnt lgkmcnt(0)
	v_cndmask_b32_e32 v8, v4, v6, vcc
	v_cndmask_b32_e32 v9, v5, v7, vcc
	v_cndmask_b32_e32 v7, v7, v5, vcc
	v_cndmask_b32_e32 v6, v6, v4, vcc
	global_store_dwordx4 v[10:11], v[6:9], off
	s_nop 1
	s_cbranch_scc0 .LBB0_480
	s_add_i32 s14, s14, s54
	s_cmpk_gt_i32 s14, 0xff
	s_barrier
	s_cbranch_scc0 .LBB0_457
.LBB0_482:
	s_waitcnt vmcnt(0)
	v_mov_b32_e32 v0, v208
	s_barrier
	s_nop 0
	v_cmp_eq_u32_e32 vcc, 0, v0
	s_and_saveexec_b64 s[0:1], vcc
	s_cbranch_execz .LBB0_512
	v_readlane_b32 s4, v234, 46
	s_lshl_b32 s4, s4, 8
	s_and_b32 s5, s50, 63
	s_add_i32 s4, s4, s5
	s_add_i32 s4, s4, 64
	s_lshl_b32 s4, s4, 6
	s_add_i32 s4, s4, 0x4000
	s_add_u32 s4, s92, s4
	s_addc_u32 s5, s93, 0
	v_mov_b32_e32 v0, 0
	s_waitcnt vmcnt(0) lgkmcnt(0)
	s_add_u32 s6, s92, 0xc000
	s_addc_u32 s7, s93, 0
	global_atomic_add v0, v210, s[6:7]
	s_and_b32 s6, s51, 7
	s_mul_i32 s6, s6, 3
	s_add_i32 s6, s6, 8
	s_lshl_b32 s6, 1, s6
	s_add_i32 s6, s6, 1
	v_mov_b32_e32 v2, s6
	global_atomic_add v0, v2, s[4:5]
	s_waitcnt vmcnt(0)

; __device__ __forceinline__ unsigned xb_ld(unsigned* p) { return __hip_atomic_load(p, __ATOMIC_RELAXED, __HIP_MEMORY_SCOPE_AGENT); }
; __device__ __forceinline__ unsigned xb_add(unsigned* p, unsigned v) { return __hip_atomic_fetch_add(p, v, __ATOMIC_RELAXED, __HIP_MEMORY_SCOPE_AGENT); }
; __device__ __forceinline__ void xcd_barrier(const XcdBarrier& b, unsigned epoch) {
;     ...
;         const unsigned old = xb_add(&bar[XB_XSUB(bx)], 1u);
;         const unsigned gen = epoch;
;         if (old + 1u == (gen + 1u) * bnloc) {
;             __builtin_amdgcn_fence(__ATOMIC_RELEASE, "agent");
;             asm volatile("s_waitcnt vmcnt(0)" ::: "memory");
;             const unsigned og = xb_add(&bar[XB_TOP], 1u);
;             const unsigned tg = epoch;
;             if (og + 1u == (tg + 1u) * bnx) xb_add(&bar[XB_TOPGEN], 1u);
;             else XB_SPIN(xb_ld(&bar[XB_TOPGEN]) == tg, bar);
;             __builtin_amdgcn_fence(__ATOMIC_ACQUIRE, "agent");
;             xb_add(&bar[XB_XGEN(bx)], 1u);
.Lgbb_done:
	v_lshrrev_b32_e32 v3, 8, v1
	v_add_u32_e32 v2, -1, v3
	v_and_b32_e32 v2, v2, v3
	v_cmp_ne_u32_e32 vcc, 0, v2
	s_cbranch_vccz .Lgbb_fast
	buffer_wbl2 sc1
	s_waitcnt vmcnt(0)
	v_readlane_b32 s4, v234, 46
	s_nop 0
	s_lshl_b32 s4, s4, 6
	s_and_b32 s5, s50, 63
	s_add_i32 s4, s4, s5
	s_lshl_b32 s4, s4, 2
	s_add_i32 s4, s4, 0xf200
	s_add_u32 s4, s92, s4
	s_addc_u32 s5, s93, 0
	global_atomic_add v0, v210, s[4:5]
	s_waitcnt vmcnt(0)
